# v23 + GEMM accumulator zeroing between tiles with v_mov_b64 pairs (64 instead of 128 moves per tile)
# speedup vs baseline: 1.0003x; 1.0003x over previous
; template <bool PERM, class Sched, class Epi>
; DI void gemm256(LAS unsigned char* lds, const Sched& S, const Epi& E, int wv_) {
;     ...
;     bool keep = false;
;     if constexpr (Sched::CHAIN) keep = E(acc, cur, wr, wc, fr, fq); else E(acc, cur, wr, wc, fr, fq);
;     if (!has_next) break;
;     if (!keep) {
; #pragma unroll
;       for (int a = 0; a < 2; ++a)
; #pragma unroll
;         for (int b = 0; b < 2; ++b)
; #pragma unroll
;           for (int m = 0; m < 4; ++m)
; #pragma unroll
;             for (int n = 0; n < 2; ++n) acc[a][b][m][n] = f4{0.f, 0.f, 0.f, 0.f};
;     }
;     cur = nxt; cA = nA; cB = nB; ++ui;
.LBB0_1508:
	v_mov_b64_e32 v[2:3], 0
	v_mov_b64_e32 v[4:5], 0
	v_mov_b64_e32 v[6:7], 0
	v_mov_b64_e32 v[8:9], 0
	v_mov_b64_e32 v[10:11], 0
	v_mov_b64_e32 v[12:13], 0
	v_mov_b64_e32 v[14:15], 0
	v_mov_b64_e32 v[16:17], 0
	v_mov_b64_e32 v[18:19], 0
	v_mov_b64_e32 v[20:21], 0
	v_mov_b64_e32 v[22:23], 0
	v_mov_b64_e32 v[24:25], 0
	v_mov_b64_e32 v[26:27], 0
	v_mov_b64_e32 v[28:29], 0
	v_mov_b64_e32 v[30:31], 0
	v_mov_b64_e32 v[32:33], 0
	v_mov_b64_e32 v[34:35], 0
	v_mov_b64_e32 v[36:37], 0
	v_mov_b64_e32 v[38:39], 0
	v_mov_b64_e32 v[40:41], 0
	v_mov_b64_e32 v[42:43], 0
	v_mov_b64_e32 v[44:45], 0
	v_mov_b64_e32 v[46:47], 0
	v_mov_b64_e32 v[48:49], 0
	v_mov_b64_e32 v[50:51], 0
	v_mov_b64_e32 v[52:53], 0
	v_mov_b64_e32 v[54:55], 0
	v_mov_b64_e32 v[56:57], 0
	v_mov_b64_e32 v[58:59], 0
	v_mov_b64_e32 v[60:61], 0
	v_mov_b64_e32 v[62:63], 0
	v_mov_b64_e32 v[64:65], 0
	v_mov_b64_e32 v[66:67], 0
	v_mov_b64_e32 v[68:69], 0
	v_mov_b64_e32 v[70:71], 0
	v_mov_b64_e32 v[72:73], 0
	v_mov_b64_e32 v[74:75], 0
	v_mov_b64_e32 v[76:77], 0
	v_mov_b64_e32 v[78:79], 0
	v_mov_b64_e32 v[80:81], 0
	v_mov_b64_e32 v[82:83], 0
	v_mov_b64_e32 v[84:85], 0
	v_mov_b64_e32 v[86:87], 0
	v_mov_b64_e32 v[88:89], 0
	v_mov_b64_e32 v[90:91], 0
	v_mov_b64_e32 v[92:93], 0
	v_mov_b64_e32 v[94:95], 0
	v_mov_b64_e32 v[96:97], 0
	v_mov_b64_e32 v[98:99], 0
	v_mov_b64_e32 v[100:101], 0
	v_mov_b64_e32 v[102:103], 0
	v_mov_b64_e32 v[104:105], 0
	v_mov_b64_e32 v[106:107], 0
	v_mov_b64_e32 v[108:109], 0
	v_mov_b64_e32 v[110:111], 0
	v_mov_b64_e32 v[112:113], 0
	v_mov_b64_e32 v[114:115], 0
	v_mov_b64_e32 v[116:117], 0
	v_mov_b64_e32 v[118:119], 0
	v_mov_b64_e32 v[120:121], 0
	v_mov_b64_e32 v[122:123], 0
	v_mov_b64_e32 v[124:125], 0
	v_mov_b64_e32 v[126:127], 0
	v_mov_b64_e32 v[128:129], 0
	s_xor_b64 s[8:9], s[8:9], -1
	s_cmp_lg_u32 s84, 0
	s_cbranch_scc1 .LBB0_1505

; template <bool PERM, class Sched, class Epi>
; DI void gemm256(LAS unsigned char* lds, const Sched& S, const Epi& E, int wv_) {
;     ...
;     bool keep = false;
;     if constexpr (Sched::CHAIN) keep = E(acc, cur, wr, wc, fr, fq); else E(acc, cur, wr, wc, fr, fq);
;     if (!has_next) break;
;     if (!keep) {
; #pragma unroll
;       for (int a = 0; a < 2; ++a)
; #pragma unroll
;         for (int b = 0; b < 2; ++b)
; #pragma unroll
;           for (int m = 0; m < 4; ++m)
; #pragma unroll
;             for (int n = 0; n < 2; ++n) acc[a][b][m][n] = f4{0.f, 0.f, 0.f, 0.f};
;     }
;     cur = nxt; cA = nA; cB = nB; ++ui;
.LBB0_1720:
	v_mov_b64_e32 v[2:3], 0
	v_mov_b64_e32 v[4:5], 0
	v_mov_b64_e32 v[6:7], 0
	v_mov_b64_e32 v[8:9], 0
	v_mov_b64_e32 v[10:11], 0
	v_mov_b64_e32 v[12:13], 0
	v_mov_b64_e32 v[14:15], 0
	v_mov_b64_e32 v[16:17], 0
	v_mov_b64_e32 v[18:19], 0
	v_mov_b64_e32 v[20:21], 0
	v_mov_b64_e32 v[22:23], 0
	v_mov_b64_e32 v[24:25], 0
	v_mov_b64_e32 v[26:27], 0
	v_mov_b64_e32 v[28:29], 0
	v_mov_b64_e32 v[30:31], 0
	v_mov_b64_e32 v[32:33], 0
	v_mov_b64_e32 v[34:35], 0
	v_mov_b64_e32 v[36:37], 0
	v_mov_b64_e32 v[38:39], 0
	v_mov_b64_e32 v[40:41], 0
	v_mov_b64_e32 v[42:43], 0
	v_mov_b64_e32 v[44:45], 0
	v_mov_b64_e32 v[46:47], 0
	v_mov_b64_e32 v[48:49], 0
	v_mov_b64_e32 v[50:51], 0
	v_mov_b64_e32 v[52:53], 0
	v_mov_b64_e32 v[54:55], 0
	v_mov_b64_e32 v[56:57], 0
	v_mov_b64_e32 v[58:59], 0
	v_mov_b64_e32 v[60:61], 0
	v_mov_b64_e32 v[62:63], 0
	v_mov_b64_e32 v[64:65], 0
	v_mov_b64_e32 v[66:67], 0
	v_mov_b64_e32 v[68:69], 0
	v_mov_b64_e32 v[70:71], 0
	v_mov_b64_e32 v[72:73], 0
	v_mov_b64_e32 v[74:75], 0
	v_mov_b64_e32 v[76:77], 0
	v_mov_b64_e32 v[78:79], 0
	v_mov_b64_e32 v[80:81], 0
	v_mov_b64_e32 v[82:83], 0
	v_mov_b64_e32 v[84:85], 0
	v_mov_b64_e32 v[86:87], 0
	v_mov_b64_e32 v[88:89], 0
	v_mov_b64_e32 v[90:91], 0
	v_mov_b64_e32 v[92:93], 0
	v_mov_b64_e32 v[94:95], 0
	v_mov_b64_e32 v[96:97], 0
	v_mov_b64_e32 v[98:99], 0
	v_mov_b64_e32 v[100:101], 0
	v_mov_b64_e32 v[102:103], 0
	v_mov_b64_e32 v[104:105], 0
	v_mov_b64_e32 v[106:107], 0
	v_mov_b64_e32 v[108:109], 0
	v_mov_b64_e32 v[110:111], 0
	v_mov_b64_e32 v[112:113], 0
	v_mov_b64_e32 v[114:115], 0
	v_mov_b64_e32 v[116:117], 0
	v_mov_b64_e32 v[118:119], 0
	v_mov_b64_e32 v[120:121], 0
	v_mov_b64_e32 v[122:123], 0
	v_mov_b64_e32 v[124:125], 0
	v_mov_b64_e32 v[126:127], 0
	v_mov_b64_e32 v[128:129], 0
